# accumulator zero-init before each GEMM unit with 64 v_mov_b64 instead of 128 v_mov_b32 (5 K-loops), on top of v9
# speedup vs baseline: 1.0001x; 1.0001x over previous
; template <class Epi, class Sched>
; __device__ __forceinline__ void gemm_phase(LAS unsigned char* lds_in, const int lda, const int ldb, const Sched& S, const Epi& E, const int WID) {
;     ...
; #pragma unroll
;         for (int a = 0; a < 2; ++a)
; #pragma unroll
;             for (int b = 0; b < 2; ++b)
; #pragma unroll
;                 for (int m = 0; m < 4; ++m)
; #pragma unroll
;                     for (int n = 0; n < 2; ++n) acc[a][b][m][n] = (f32x4){0.f, 0.f, 0.f, 0.f};
;         cur = nxt; cA = nA; cB = nB; ++ui;
.LBB0_150:
	s_add_u32 s6, s6, 0x200080
	s_addc_u32 s7, s7, 0
	s_add_u32 s5, s20, 0x100
	v_mov_b32_e32 v2, 0
	s_addc_u32 s15, s21, 0
	s_mov_b32 vcc_lo, -2
	s_waitcnt lgkmcnt(0)
	v_mov_b64_e32 v[2:3], 0
	v_mov_b64_e32 v[4:5], 0
	v_mov_b64_e32 v[6:7], 0
	v_mov_b64_e32 v[8:9], 0
	v_mov_b64_e32 v[10:11], 0
	v_mov_b64_e32 v[12:13], 0
	v_mov_b64_e32 v[14:15], 0
	v_mov_b64_e32 v[16:17], 0
	v_mov_b64_e32 v[18:19], 0
	v_mov_b64_e32 v[20:21], 0
	v_mov_b64_e32 v[22:23], 0
	v_mov_b64_e32 v[24:25], 0
	v_mov_b64_e32 v[26:27], 0
	v_mov_b64_e32 v[28:29], 0
	v_mov_b64_e32 v[30:31], 0
	v_mov_b64_e32 v[32:33], 0
	v_mov_b64_e32 v[34:35], 0
	v_mov_b64_e32 v[36:37], 0
	v_mov_b64_e32 v[38:39], 0
	v_mov_b64_e32 v[40:41], 0
	v_mov_b64_e32 v[42:43], 0
	v_mov_b64_e32 v[44:45], 0
	v_mov_b64_e32 v[46:47], 0
	v_mov_b64_e32 v[48:49], 0
	v_mov_b64_e32 v[50:51], 0
	v_mov_b64_e32 v[52:53], 0
	v_mov_b64_e32 v[54:55], 0
	v_mov_b64_e32 v[56:57], 0
	v_mov_b64_e32 v[58:59], 0
	v_mov_b64_e32 v[60:61], 0
	v_mov_b64_e32 v[62:63], 0
	v_mov_b64_e32 v[64:65], 0
	v_mov_b64_e32 v[74:75], 0
	v_mov_b64_e32 v[76:77], 0
	v_mov_b64_e32 v[78:79], 0
	v_mov_b64_e32 v[80:81], 0
	v_mov_b64_e32 v[86:87], 0
	v_mov_b64_e32 v[88:89], 0
	v_mov_b64_e32 v[90:91], 0
	v_mov_b64_e32 v[92:93], 0
	v_mov_b64_e32 v[98:99], 0
	v_mov_b64_e32 v[100:101], 0
	v_mov_b64_e32 v[102:103], 0
	v_mov_b64_e32 v[104:105], 0
	v_mov_b64_e32 v[110:111], 0
	v_mov_b64_e32 v[112:113], 0
	v_mov_b64_e32 v[114:115], 0
	v_mov_b64_e32 v[116:117], 0
	v_mov_b64_e32 v[122:123], 0
	v_mov_b64_e32 v[124:125], 0
	v_mov_b64_e32 v[126:127], 0
	v_mov_b64_e32 v[128:129], 0
	v_mov_b64_e32 v[134:135], 0
	v_mov_b64_e32 v[136:137], 0
	v_mov_b64_e32 v[138:139], 0
	v_mov_b64_e32 v[140:141], 0
	v_mov_b64_e32 v[146:147], 0
	v_mov_b64_e32 v[148:149], 0
	v_mov_b64_e32 v[150:151], 0
	v_mov_b64_e32 v[152:153], 0
	v_mov_b64_e32 v[158:159], 0
	v_mov_b64_e32 v[160:161], 0
	v_mov_b64_e32 v[162:163], 0
	v_mov_b64_e32 v[164:165], 0

; template <class Epi, class Sched>
; __device__ __forceinline__ void gemm_phase(LAS unsigned char* lds_in, const int lda, const int ldb, const Sched& S, const Epi& E, const int WID) {
;     ...
; #pragma unroll
;         for (int a = 0; a < 2; ++a)
; #pragma unroll
;             for (int b = 0; b < 2; ++b)
; #pragma unroll
;                 for (int m = 0; m < 4; ++m)
; #pragma unroll
;                     for (int n = 0; n < 2; ++n) acc[a][b][m][n] = (f32x4){0.f, 0.f, 0.f, 0.f};
;         cur = nxt; cA = nA; cB = nB; ++ui;
.LBB0_266:
	s_add_u32 s10, s10, 0x80080
	s_addc_u32 s11, s11, 0
	s_add_u32 s3, s12, 0x100
	v_mov_b32_e32 v2, 0
	s_addc_u32 s94, s13, 0
	s_mov_b32 s95, -2
	v_mov_b64_e32 v[2:3], 0
	v_mov_b64_e32 v[4:5], 0
	v_mov_b64_e32 v[6:7], 0
	v_mov_b64_e32 v[8:9], 0
	v_mov_b64_e32 v[10:11], 0
	v_mov_b64_e32 v[12:13], 0
	v_mov_b64_e32 v[14:15], 0
	v_mov_b64_e32 v[16:17], 0
	v_mov_b64_e32 v[18:19], 0
	v_mov_b64_e32 v[20:21], 0
	v_mov_b64_e32 v[22:23], 0
	v_mov_b64_e32 v[24:25], 0
	v_mov_b64_e32 v[26:27], 0
	v_mov_b64_e32 v[28:29], 0
	v_mov_b64_e32 v[30:31], 0
	v_mov_b64_e32 v[32:33], 0
	v_mov_b64_e32 v[34:35], 0
	v_mov_b64_e32 v[36:37], 0
	v_mov_b64_e32 v[38:39], 0
	v_mov_b64_e32 v[40:41], 0
	v_mov_b64_e32 v[42:43], 0
	v_mov_b64_e32 v[44:45], 0
	v_mov_b64_e32 v[46:47], 0
	v_mov_b64_e32 v[48:49], 0
	v_mov_b64_e32 v[50:51], 0
	v_mov_b64_e32 v[52:53], 0
	v_mov_b64_e32 v[54:55], 0
	v_mov_b64_e32 v[56:57], 0
	v_mov_b64_e32 v[58:59], 0
	v_mov_b64_e32 v[60:61], 0
	v_mov_b64_e32 v[62:63], 0
	v_mov_b64_e32 v[64:65], 0
	v_mov_b64_e32 v[66:67], 0
	v_mov_b64_e32 v[68:69], 0
	v_mov_b64_e32 v[70:71], 0
	v_mov_b64_e32 v[72:73], 0
	v_mov_b64_e32 v[74:75], 0
	v_mov_b64_e32 v[76:77], 0
	v_mov_b64_e32 v[78:79], 0
	v_mov_b64_e32 v[80:81], 0
	v_mov_b64_e32 v[82:83], 0
	v_mov_b64_e32 v[84:85], 0
	v_mov_b64_e32 v[86:87], 0
	v_mov_b64_e32 v[88:89], 0
	v_mov_b64_e32 v[90:91], 0
	v_mov_b64_e32 v[92:93], 0
	v_mov_b64_e32 v[94:95], 0
	v_mov_b64_e32 v[96:97], 0
	v_mov_b64_e32 v[98:99], 0
	v_mov_b64_e32 v[100:101], 0
	v_mov_b64_e32 v[102:103], 0
	v_mov_b64_e32 v[104:105], 0
	v_mov_b64_e32 v[106:107], 0
	v_mov_b64_e32 v[108:109], 0
	v_mov_b64_e32 v[110:111], 0
	v_mov_b64_e32 v[112:113], 0
	v_mov_b64_e32 v[114:115], 0
	v_mov_b64_e32 v[116:117], 0
	v_mov_b64_e32 v[118:119], 0
	v_mov_b64_e32 v[120:121], 0
	v_mov_b64_e32 v[122:123], 0
	v_mov_b64_e32 v[124:125], 0
	v_mov_b64_e32 v[126:127], 0
	v_mov_b64_e32 v[128:129], 0

; template <class Epi, class Sched>
; __device__ __forceinline__ void gemm_phase(LAS unsigned char* lds_in, const int lda, const int ldb, const Sched& S, const Epi& E, const int WID) {
;     ...
; #pragma unroll
;         for (int a = 0; a < 2; ++a)
; #pragma unroll
;             for (int b = 0; b < 2; ++b)
; #pragma unroll
;                 for (int m = 0; m < 4; ++m)
; #pragma unroll
;                     for (int n = 0; n < 2; ++n) acc[a][b][m][n] = (f32x4){0.f, 0.f, 0.f, 0.f};
;         cur = nxt; cA = nA; cB = nB; ++ui;
.LBB0_300:
	s_add_u32 s12, s12, 0x80080
	s_addc_u32 s13, s13, 0
	s_add_u32 s5, s14, 0x100
	v_mov_b32_e32 v2, 0
	s_addc_u32 s11, s15, 0
	s_mov_b32 s97, -2
	s_waitcnt lgkmcnt(0)
	v_mov_b64_e32 v[2:3], 0
	v_mov_b64_e32 v[4:5], 0
	v_mov_b64_e32 v[6:7], 0
	v_mov_b64_e32 v[8:9], 0
	v_mov_b64_e32 v[10:11], 0
	v_mov_b64_e32 v[12:13], 0
	v_mov_b64_e32 v[14:15], 0
	v_mov_b64_e32 v[16:17], 0
	v_mov_b64_e32 v[18:19], 0
	v_mov_b64_e32 v[20:21], 0
	v_mov_b64_e32 v[22:23], 0
	v_mov_b64_e32 v[24:25], 0
	v_mov_b64_e32 v[26:27], 0
	v_mov_b64_e32 v[28:29], 0
	v_mov_b64_e32 v[30:31], 0
	v_mov_b64_e32 v[32:33], 0
	v_mov_b64_e32 v[34:35], 0
	v_mov_b64_e32 v[36:37], 0
	v_mov_b64_e32 v[38:39], 0
	v_mov_b64_e32 v[40:41], 0
	v_mov_b64_e32 v[42:43], 0
	v_mov_b64_e32 v[44:45], 0
	v_mov_b64_e32 v[46:47], 0
	v_mov_b64_e32 v[48:49], 0
	v_mov_b64_e32 v[50:51], 0
	v_mov_b64_e32 v[52:53], 0
	v_mov_b64_e32 v[54:55], 0
	v_mov_b64_e32 v[56:57], 0
	v_mov_b64_e32 v[58:59], 0
	v_mov_b64_e32 v[60:61], 0
	v_mov_b64_e32 v[62:63], 0
	v_mov_b64_e32 v[64:65], 0
	v_mov_b64_e32 v[66:67], 0
	v_mov_b64_e32 v[68:69], 0
	v_mov_b64_e32 v[70:71], 0
	v_mov_b64_e32 v[72:73], 0
	v_mov_b64_e32 v[74:75], 0
	v_mov_b64_e32 v[76:77], 0
	v_mov_b64_e32 v[78:79], 0
	v_mov_b64_e32 v[80:81], 0
	v_mov_b64_e32 v[82:83], 0
	v_mov_b64_e32 v[84:85], 0
	v_mov_b64_e32 v[86:87], 0
	v_mov_b64_e32 v[88:89], 0
	v_mov_b64_e32 v[90:91], 0
	v_mov_b64_e32 v[92:93], 0
	v_mov_b64_e32 v[94:95], 0
	v_mov_b64_e32 v[96:97], 0
	v_mov_b64_e32 v[98:99], 0
	v_mov_b64_e32 v[100:101], 0
	v_mov_b64_e32 v[102:103], 0
	v_mov_b64_e32 v[104:105], 0
	v_mov_b64_e32 v[106:107], 0
	v_mov_b64_e32 v[108:109], 0
	v_mov_b64_e32 v[110:111], 0
	v_mov_b64_e32 v[112:113], 0
	v_mov_b64_e32 v[122:123], 0
	v_mov_b64_e32 v[124:125], 0
	v_mov_b64_e32 v[126:127], 0
	v_mov_b64_e32 v[128:129], 0
	v_mov_b64_e32 v[150:151], 0
	v_mov_b64_e32 v[152:153], 0
	v_mov_b64_e32 v[154:155], 0
	v_mov_b64_e32 v[156:157], 0

; template <class Epi, class Sched>
; __device__ __forceinline__ void gemm_phase(LAS unsigned char* lds_in, const int lda, const int ldb, const Sched& S, const Epi& E, const int WID) {
;     ...
; #pragma unroll
;         for (int a = 0; a < 2; ++a)
; #pragma unroll
;             for (int b = 0; b < 2; ++b)
; #pragma unroll
;                 for (int m = 0; m < 4; ++m)
; #pragma unroll
;                     for (int n = 0; n < 2; ++n) acc[a][b][m][n] = (f32x4){0.f, 0.f, 0.f, 0.f};
;         cur = nxt; cA = nA; cB = nB; ++ui;
.LBB0_921:
	s_add_u32 s14, s14, 0x80080
	s_addc_u32 s15, s15, 0
	s_add_u32 s7, s16, 0x100
	v_mov_b32_e32 v2, 0
	s_addc_u32 s13, s17, 0
	s_mov_b32 vcc_lo, -2
	v_mov_b64_e32 v[2:3], 0
	v_mov_b64_e32 v[4:5], 0
	v_mov_b64_e32 v[6:7], 0
	v_mov_b64_e32 v[8:9], 0
	v_mov_b64_e32 v[10:11], 0
	v_mov_b64_e32 v[12:13], 0
	v_mov_b64_e32 v[14:15], 0
	v_mov_b64_e32 v[16:17], 0
	v_mov_b64_e32 v[18:19], 0
	v_mov_b64_e32 v[20:21], 0
	v_mov_b64_e32 v[22:23], 0
	v_mov_b64_e32 v[24:25], 0
	v_mov_b64_e32 v[26:27], 0
	v_mov_b64_e32 v[28:29], 0
	v_mov_b64_e32 v[30:31], 0
	v_mov_b64_e32 v[32:33], 0
	v_mov_b64_e32 v[34:35], 0
	v_mov_b64_e32 v[36:37], 0
	v_mov_b64_e32 v[38:39], 0
	v_mov_b64_e32 v[40:41], 0
	v_mov_b64_e32 v[42:43], 0
	v_mov_b64_e32 v[44:45], 0
	v_mov_b64_e32 v[46:47], 0
	v_mov_b64_e32 v[48:49], 0
	v_mov_b64_e32 v[50:51], 0
	v_mov_b64_e32 v[52:53], 0
	v_mov_b64_e32 v[54:55], 0
	v_mov_b64_e32 v[56:57], 0
	v_mov_b64_e32 v[58:59], 0
	v_mov_b64_e32 v[60:61], 0
	v_mov_b64_e32 v[62:63], 0
	v_mov_b64_e32 v[64:65], 0
	v_mov_b64_e32 v[66:67], 0
	v_mov_b64_e32 v[68:69], 0
	v_mov_b64_e32 v[70:71], 0
	v_mov_b64_e32 v[72:73], 0
	v_mov_b64_e32 v[74:75], 0
	v_mov_b64_e32 v[76:77], 0
	v_mov_b64_e32 v[78:79], 0
	v_mov_b64_e32 v[80:81], 0
	v_mov_b64_e32 v[82:83], 0
	v_mov_b64_e32 v[84:85], 0
	v_mov_b64_e32 v[86:87], 0
	v_mov_b64_e32 v[88:89], 0
	v_mov_b64_e32 v[90:91], 0
	v_mov_b64_e32 v[92:93], 0
	v_mov_b64_e32 v[94:95], 0
	v_mov_b64_e32 v[96:97], 0
	v_mov_b64_e32 v[98:99], 0
	v_mov_b64_e32 v[100:101], 0
	v_mov_b64_e32 v[102:103], 0
	v_mov_b64_e32 v[104:105], 0
	v_mov_b64_e32 v[106:107], 0
	v_mov_b64_e32 v[108:109], 0
	v_mov_b64_e32 v[110:111], 0
	v_mov_b64_e32 v[112:113], 0
	v_mov_b64_e32 v[114:115], 0
	v_mov_b64_e32 v[116:117], 0
	v_mov_b64_e32 v[118:119], 0
	v_mov_b64_e32 v[120:121], 0
	v_mov_b64_e32 v[122:123], 0
	v_mov_b64_e32 v[124:125], 0
	v_mov_b64_e32 v[126:127], 0
	v_mov_b64_e32 v[128:129], 0

; #define PG8_SCHED __builtin_amdgcn_sched_barrier(0)
; template <class Epi, class Sched>
; __device__ __forceinline__ void gemm_phase(LAS unsigned char* lds_in, const int lda, const int ldb, const Sched& S, const Epi& E, const int WID) {
;     ...
;         for (int sg = 0; sg < (Epi::HAS_MID ? 3 : 1); ++sg) {
;         const int tb = Epi::HAS_MID ? (sg == 0 ? 0 : (sg == 1 ? 16 : 24)) : 0, te = Epi::HAS_MID ? (sg == 0 ? 16 : (sg == 1 ? 24 : nt)) : nt;
;         if constexpr (Epi::HAS_MID) { if (sg > 0) { PG8_SCHED; E.mid(acc, cur, tb, wr, wc, fr, fq); PG8_SCHED; } }
;         for (int t = tb; t < te; t += 2) {
;     ...
; #pragma unroll
;         for (int a = 0; a < 2; ++a)
; #pragma unroll
;             for (int b = 0; b < 2; ++b)
; #pragma unroll
;                 for (int m = 0; m < 4; ++m)
; #pragma unroll
;                     for (int n = 0; n < 2; ++n) acc[a][b][m][n] = (f32x4){0.f, 0.f, 0.f, 0.f};
;         cur = nxt; cA = nA; cB = nB; ++ui;
.LBB0_1039:
	s_add_u32 s18, s18, 0x80080
	s_addc_u32 s19, s19, 0
	s_add_u32 s1, s20, 0x100
	v_mov_b32_e32 v2, 0
	s_addc_u32 s11, s21, 0
	s_mov_b32 s70, -2
	s_cmp_eq_u32 s99, 0
	s_cselect_b32 s32, 28, 12
	v_mov_b64_e32 v[2:3], 0
	v_mov_b64_e32 v[4:5], 0
	v_mov_b64_e32 v[6:7], 0
	v_mov_b64_e32 v[8:9], 0
	v_mov_b64_e32 v[10:11], 0
	v_mov_b64_e32 v[12:13], 0
	v_mov_b64_e32 v[14:15], 0
	v_mov_b64_e32 v[16:17], 0
	v_mov_b64_e32 v[18:19], 0
	v_mov_b64_e32 v[20:21], 0
	v_mov_b64_e32 v[22:23], 0
	v_mov_b64_e32 v[24:25], 0
	v_mov_b64_e32 v[26:27], 0
	v_mov_b64_e32 v[28:29], 0
	v_mov_b64_e32 v[30:31], 0
	v_mov_b64_e32 v[32:33], 0
	v_mov_b64_e32 v[34:35], 0
	v_mov_b64_e32 v[36:37], 0
	v_mov_b64_e32 v[38:39], 0
	v_mov_b64_e32 v[40:41], 0
	v_mov_b64_e32 v[42:43], 0
	v_mov_b64_e32 v[44:45], 0
	v_mov_b64_e32 v[46:47], 0
	v_mov_b64_e32 v[48:49], 0
	v_mov_b64_e32 v[50:51], 0
	v_mov_b64_e32 v[52:53], 0
	v_mov_b64_e32 v[54:55], 0
	v_mov_b64_e32 v[56:57], 0
	v_mov_b64_e32 v[58:59], 0
	v_mov_b64_e32 v[60:61], 0
	v_mov_b64_e32 v[62:63], 0
	v_mov_b64_e32 v[64:65], 0
	v_mov_b64_e32 v[66:67], 0
	v_mov_b64_e32 v[68:69], 0
	v_mov_b64_e32 v[70:71], 0
	v_mov_b64_e32 v[72:73], 0
	v_mov_b64_e32 v[74:75], 0
	v_mov_b64_e32 v[76:77], 0
	v_mov_b64_e32 v[78:79], 0
	v_mov_b64_e32 v[80:81], 0
	v_mov_b64_e32 v[82:83], 0
	v_mov_b64_e32 v[84:85], 0
	v_mov_b64_e32 v[86:87], 0
	v_mov_b64_e32 v[88:89], 0
	v_mov_b64_e32 v[90:91], 0
	v_mov_b64_e32 v[92:93], 0
	v_mov_b64_e32 v[94:95], 0
	v_mov_b64_e32 v[96:97], 0
	v_mov_b64_e32 v[98:99], 0
	v_mov_b64_e32 v[100:101], 0
	v_mov_b64_e32 v[102:103], 0
	v_mov_b64_e32 v[104:105], 0
	v_mov_b64_e32 v[106:107], 0
	v_mov_b64_e32 v[108:109], 0
	v_mov_b64_e32 v[110:111], 0
	v_mov_b64_e32 v[112:113], 0
	v_mov_b64_e32 v[114:115], 0
	v_mov_b64_e32 v[116:117], 0
	v_mov_b64_e32 v[118:119], 0
	v_mov_b64_e32 v[120:121], 0
	v_mov_b64_e32 v[122:123], 0
	v_mov_b64_e32 v[124:125], 0
	v_mov_b64_e32 v[126:127], 0
	v_mov_b64_e32 v[128:129], 0
